# HGRN2: gate loads of the y epilogue issued at the end of step 2 (behind the prefetch) into dedicated registers instead of at the start of step 4
# baseline (speedup 1.0000x reference)
.LBB0_1168:
	s_or_b64 exec, exec, s[6:7]
	s_waitcnt lgkmcnt(0)
	ds_read_b128 v[114:117], v150 offset:52224
	ds_read_b128 v[118:121], v150 offset:52288
	v_add_u32_e32 v67, v137, v133
	ds_read_b128 v[160:163], v151
	ds_read_b128 v[164:167], v67
	ds_read_b128 v[168:171], v67 offset:2304
	ds_read_b128 v[172:175], v67 offset:64
	ds_read_b128 v[176:179], v67 offset:2368
	v_ashrrev_i32_e32 v67, 31, v66
	s_waitcnt lgkmcnt(4)
	v_pk_mul_f32 v[18:19], v[18:19], v[160:161]
	v_pk_mul_f32 v[20:21], v[20:21], v[162:163]
	v_pk_mul_f32 v[30:31], v[30:31], v[160:161]
	v_pk_mul_f32 v[32:33], v[32:33], v[162:163]
	s_waitcnt lgkmcnt(3)
	v_mfma_f32_16x16x32_bf16 v[18:21], v[114:117], v[164:167], v[18:21]
	s_waitcnt lgkmcnt(2)
	v_mfma_f32_16x16x32_bf16 v[30:33], v[114:117], v[168:171], v[30:33]
	s_waitcnt lgkmcnt(1)
	v_mfma_f32_16x16x32_bf16 v[18:21], v[118:121], v[172:175], v[18:21]
	s_waitcnt lgkmcnt(0)
	v_mfma_f32_16x16x32_bf16 v[30:33], v[118:121], v[176:179], v[30:33]
	ds_read_b128 v[164:167], v152
	ds_read_b128 v[168:171], v152 offset:2304
	ds_read_b128 v[172:175], v152 offset:64
	ds_read_b128 v[176:179], v152 offset:2368
	v_pk_mul_f32 v[34:35], v[34:35], v[160:161]
	v_pk_mul_f32 v[36:37], v[36:37], v[162:163]
	v_pk_mul_f32 v[38:39], v[38:39], v[160:161]
	v_pk_mul_f32 v[40:41], v[40:41], v[162:163]
	s_waitcnt lgkmcnt(3)
	v_mfma_f32_16x16x32_bf16 v[34:37], v[114:117], v[164:167], v[34:37]
	s_waitcnt lgkmcnt(2)
	v_mfma_f32_16x16x32_bf16 v[38:41], v[114:117], v[168:171], v[38:41]
	s_waitcnt lgkmcnt(1)
	v_mfma_f32_16x16x32_bf16 v[34:37], v[118:121], v[172:175], v[34:37]
	s_waitcnt lgkmcnt(0)
	v_mfma_f32_16x16x32_bf16 v[38:41], v[118:121], v[176:179], v[38:41]
	ds_read_b128 v[164:167], v153
	ds_read_b128 v[168:171], v153 offset:2304
	ds_read_b128 v[172:175], v153 offset:64
	ds_read_b128 v[176:179], v153 offset:2368
	v_pk_mul_f32 v[42:43], v[42:43], v[160:161]
	v_pk_mul_f32 v[44:45], v[44:45], v[162:163]
	v_pk_mul_f32 v[50:51], v[50:51], v[160:161]
	v_pk_mul_f32 v[52:53], v[52:53], v[162:163]
	s_waitcnt lgkmcnt(3)
	v_mfma_f32_16x16x32_bf16 v[42:45], v[114:117], v[164:167], v[42:45]
	s_waitcnt lgkmcnt(2)
	v_mfma_f32_16x16x32_bf16 v[50:53], v[114:117], v[168:171], v[50:53]
	s_waitcnt lgkmcnt(1)
	v_mfma_f32_16x16x32_bf16 v[42:45], v[118:121], v[172:175], v[42:45]
	s_waitcnt lgkmcnt(0)
	v_mfma_f32_16x16x32_bf16 v[50:53], v[118:121], v[176:179], v[50:53]
	ds_read_b128 v[164:167], v154
	ds_read_b128 v[168:171], v154 offset:2304
	ds_read_b128 v[172:175], v154 offset:64
	ds_read_b128 v[176:179], v154 offset:2368
	v_pk_mul_f32 v[46:47], v[46:47], v[160:161]
	v_pk_mul_f32 v[48:49], v[48:49], v[162:163]
	v_pk_mul_f32 v[54:55], v[54:55], v[160:161]
	v_pk_mul_f32 v[56:57], v[56:57], v[162:163]
	s_waitcnt lgkmcnt(3)
	v_mfma_f32_16x16x32_bf16 v[46:49], v[114:117], v[164:167], v[46:49]
	s_waitcnt lgkmcnt(0)
	s_barrier
	v_mfma_f32_16x16x32_bf16 v[54:57], v[114:117], v[168:171], v[54:57]
	ds_read2st64_b32 v[114:115], v136 offset1:1
	v_lshlrev_b64 v[66:67], 13, v[66:67]
	s_waitcnt vmcnt(3)
	v_mov_b32_e32 v64, v180
	v_mov_b32_e32 v65, v181
	v_lshlrev_b32_e32 v116, 16, v64
	v_and_b32_e32 v117, 0xffff0000, v64
	v_lshl_add_u64 v[66:67], s[4:5], 0, v[66:67]
	s_waitcnt lgkmcnt(0)
	v_add_f32_e32 v114, v114, v115
	v_fmamk_f32 v114, v114, 0x3c000000, v197
	v_cmp_gt_f32_e32 vcc, s81, v114
	v_mul_f32_e32 v115, 0x4b800000, v114
	v_lshl_add_u64 v[66:67], v[66:67], 0, s[36:37]
	v_cndmask_b32_e32 v114, v114, v115, vcc
	v_rsq_f32_e32 v114, v114
	s_mov_b64 s[6:7], 0x29401000
	v_lshl_add_u64 v[66:67], v[66:67], 0, s[6:7]
	v_mfma_f32_16x16x32_bf16 v[46:49], v[118:121], v[172:175], v[46:49]
	v_mul_f32_e32 v115, 0x45800000, v114
	v_cndmask_b32_e32 v114, v114, v115, vcc
	v_pk_mul_f32 v[70:71], v[70:71], v[114:115] op_sel_hi:[1,0]
	v_pk_mul_f32 v[68:69], v[68:69], v[114:115] op_sel_hi:[1,0]
	v_pk_mul_f32 v[70:71], v[2:3], v[70:71]
	v_pk_mul_f32 v[68:69], v[4:5], v[68:69]
	v_pk_mul_f32 v[70:71], v[70:71], v[116:117]
	v_mfma_f32_16x16x32_bf16 v[54:57], v[118:121], v[176:179], v[54:57]
	v_cvt_pk_bf16_f32 v64, v70, v71
	v_lshlrev_b32_e32 v70, 16, v65
	v_and_b32_e32 v71, 0xffff0000, v65
	v_pk_mul_f32 v[68:69], v[68:69], v[70:71]
	s_waitcnt vmcnt(2)
	v_mov_b32_e32 v62, v182
	v_mov_b32_e32 v63, v183
	v_lshlrev_b32_e32 v70, 16, v62
	v_cvt_pk_bf16_f32 v65, v68, v69
	v_lshl_add_u64 v[68:69], v[94:95], 1, v[66:67]
	global_store_dwordx2 v[68:69], v[64:65], off
	v_pk_mul_f32 v[64:65], v[104:105], v[114:115] op_sel_hi:[1,0]
	v_and_b32_e32 v71, 0xffff0000, v62
	v_pk_mul_f32 v[64:65], v[6:7], v[64:65]
	v_pk_mul_f32 v[68:69], v[72:73], v[114:115] op_sel_hi:[1,0]
	v_pk_mul_f32 v[64:65], v[64:65], v[70:71]
	v_pk_mul_f32 v[68:69], v[8:9], v[68:69]
	v_cvt_pk_bf16_f32 v62, v64, v65
	v_lshlrev_b32_e32 v64, 16, v63
	v_and_b32_e32 v65, 0xffff0000, v63
	v_pk_mul_f32 v[64:65], v[68:69], v[64:65]
	s_waitcnt vmcnt(2)
	v_mov_b32_e32 v60, v184
	v_mov_b32_e32 v61, v185
	v_lshlrev_b32_e32 v68, 16, v60
	v_cvt_pk_bf16_f32 v63, v64, v65
	v_lshl_add_u64 v[64:65], v[98:99], 1, v[66:67]
	global_store_dwordx2 v[64:65], v[62:63], off offset:32
	v_pk_mul_f32 v[62:63], v[108:109], v[114:115] op_sel_hi:[1,0]
	v_and_b32_e32 v69, 0xffff0000, v60
	v_pk_mul_f32 v[62:63], v[10:11], v[62:63]
	v_pk_mul_f32 v[66:67], v[106:107], v[114:115] op_sel_hi:[1,0]
	v_pk_mul_f32 v[62:63], v[62:63], v[68:69]
	v_pk_mul_f32 v[66:67], v[12:13], v[66:67]
	v_cvt_pk_bf16_f32 v60, v62, v63
	v_lshlrev_b32_e32 v62, 16, v61
	v_and_b32_e32 v63, 0xffff0000, v61
	v_pk_mul_f32 v[62:63], v[66:67], v[62:63]
	s_waitcnt vmcnt(2)
	v_mov_b32_e32 v58, v186
	v_mov_b32_e32 v59, v187
	v_lshlrev_b32_e32 v66, 16, v58
	v_cvt_pk_bf16_f32 v61, v62, v63
	global_store_dwordx2 v[64:65], v[60:61], off offset:64
	v_pk_mul_f32 v[60:61], v[112:113], v[114:115] op_sel_hi:[1,0]
	v_and_b32_e32 v67, 0xffff0000, v58
	v_pk_mul_f32 v[60:61], v[14:15], v[60:61]
	v_pk_mul_f32 v[62:63], v[110:111], v[114:115] op_sel_hi:[1,0]
	v_pk_mul_f32 v[60:61], v[60:61], v[66:67]
	v_pk_mul_f32 v[62:63], v[16:17], v[62:63]
	v_cvt_pk_bf16_f32 v58, v60, v61
	v_lshlrev_b32_e32 v60, 16, v59
	v_and_b32_e32 v61, 0xffff0000, v59
	v_pk_mul_f32 v[60:61], v[62:63], v[60:61]
	s_cmp_lg_u32 s3, 32
	v_cvt_pk_bf16_f32 v59, v60, v61
	global_store_dwordx2 v[64:65], v[58:59], off offset:96
	v_cvt_pk_bf16_f32 v58, v18, v19
	v_cvt_pk_bf16_f32 v59, v20, v21
	ds_write_b64 v155, v[58:59]
	v_cvt_pk_bf16_f32 v58, v30, v31
	v_cvt_pk_bf16_f32 v59, v32, v33
	ds_write_b64 v155, v[58:59] offset:4352
	v_cvt_pk_bf16_f32 v58, v34, v35
	v_cvt_pk_bf16_f32 v59, v36, v37
	ds_write_b64 v155, v[58:59] offset:8704
	v_cvt_pk_bf16_f32 v58, v38, v39
	v_cvt_pk_bf16_f32 v59, v40, v41
	ds_write_b64 v155, v[58:59] offset:13056
	v_cvt_pk_bf16_f32 v58, v42, v43
	v_cvt_pk_bf16_f32 v59, v44, v45
	ds_write_b64 v155, v[58:59] offset:17408
	v_cvt_pk_bf16_f32 v58, v50, v51
	v_cvt_pk_bf16_f32 v59, v52, v53
	ds_write_b64 v155, v[58:59] offset:21760
	v_cvt_pk_bf16_f32 v58, v46, v47
	v_cvt_pk_bf16_f32 v59, v48, v49
	ds_write_b64 v155, v[58:59] offset:26112
	v_cvt_pk_bf16_f32 v58, v54, v55
	v_cvt_pk_bf16_f32 v59, v56, v57
	s_mov_b32 s2, s3
	ds_write_b64 v155, v[58:59] offset:30464
	s_cbranch_scc0 .LBB0_1179

.Lhg_gate:
	v_lshl_add_u32 v242, s2, 6, v138
	v_mov_b64_e32 v[238:239], s[0:1]
	v_mad_i64_i32 v[238:239], s[6:7], v242, s28, v[238:239]
	v_readlane_b32 s6, v254, 47
	v_lshl_add_u64 v[238:239], v[238:239], 0, s[36:37]
	v_lshl_add_u64 v[238:239], v[88:89], 1, v[238:239]
	s_nop 0
	s_lshl_b32 s6, s6, 1
	s_mov_b32 s7, s37
	v_lshl_add_u64 v[238:239], v[238:239], 0, s[6:7]
	s_mov_b64 s[6:7], 0x5000
	v_lshl_add_u64 v[240:241], v[238:239], 0, s[6:7]
	v_add_co_u32_e32 v238, vcc, s13, v238
	s_nop 1
	v_addc_co_u32_e32 v239, vcc, 0, v239, vcc
	global_load_dwordx2 v[180:181], v[238:239], off
	global_load_dwordx2 v[182:183], v[240:241], off offset:32
	global_load_dwordx2 v[184:185], v[240:241], off offset:64
	global_load_dwordx2 v[186:187], v[240:241], off offset:96

.LBB0_1177:
	v_lshl_add_u32 v66, s2, 6, v138
	v_mov_b64_e32 v[58:59], s[0:1]
	v_mad_i64_i32 v[58:59], s[6:7], v66, s28, v[58:59]
	v_readlane_b32 s6, v254, 47
	v_lshl_add_u64 v[58:59], v[58:59], 0, s[36:37]
	v_readlane_b32 s7, v254, 48
	v_lshl_add_u64 v[58:59], v[88:89], 1, v[58:59]
	s_lshl_b32 s6, s6, 1
	s_mov_b32 s7, s37
	v_lshl_add_u64 v[58:59], v[58:59], 0, s[6:7]
	s_mov_b64 s[6:7], 0x5000
	v_lshl_add_u64 v[68:69], v[58:59], 0, s[6:7]
	v_add_co_u32_e32 v58, vcc, s13, v58
	s_waitcnt lgkmcnt(0)
	s_nop 0
	v_addc_co_u32_e32 v59, vcc, 0, v59, vcc
	s_barrier
	ds_read_b128 v[110:113], v145
	ds_read_b128 v[114:117], v145 offset:64
	ds_read_b128 v[118:121], v146 offset:17408
	ds_read_b128 v[160:163], v146 offset:17472
	ds_read_b128 v[164:167], v146 offset:17536
	ds_read_b128 v[168:171], v146 offset:17600
	ds_read_b128 v[68:71], v147
	ds_read_b128 v[104:107], v147 offset:64
	ds_read_b128 v[172:175], v148
	ds_read_b128 v[176:179], v148 offset:64
	ds_read_b128 v[188:191], v148 offset:128
	ds_read_b128 v[192:195], v148 offset:192
	s_waitcnt lgkmcnt(5)
	v_mfma_f32_16x16x32_bf16 v[68:71], v[68:71], v[110:113], 0
	s_waitcnt lgkmcnt(3)
	v_mfma_f32_16x16x32_bf16 v[172:175], v[172:175], v[118:121], 0
	v_mfma_f32_16x16x32_bf16 v[68:71], v[104:107], v[114:117], v[68:71]
	s_waitcnt lgkmcnt(2)
	v_mfma_f32_16x16x32_bf16 v[104:107], v[176:179], v[160:163], v[172:175]
	s_waitcnt lgkmcnt(1)
	v_mfma_f32_16x16x32_bf16 v[70:73], v[188:191], v[164:167], v[68:71]
	s_waitcnt lgkmcnt(0)
	v_mfma_f32_16x16x32_bf16 v[104:107], v[192:195], v[168:171], v[104:107]
	s_nop 7
	v_pk_add_f32 v[68:69], v[72:73], v[106:107]
	v_pk_add_f32 v[70:71], v[70:71], v[104:105]
	ds_read_b128 v[104:107], v147 offset:2304
	ds_read_b128 v[172:175], v147 offset:2368
	ds_read_b128 v[176:179], v148 offset:4352
	ds_read_b128 v[188:191], v148 offset:4416
	ds_read_b128 v[192:195], v148 offset:4480
	ds_read_b128 v[206:209], v148 offset:4544
	s_waitcnt lgkmcnt(5)
	v_mfma_f32_16x16x32_bf16 v[104:107], v[104:107], v[110:113], 0
	s_waitcnt lgkmcnt(3)
	v_mfma_f32_16x16x32_bf16 v[176:179], v[176:179], v[118:121], 0
	v_mfma_f32_16x16x32_bf16 v[104:107], v[172:175], v[114:117], v[104:107]
	s_waitcnt lgkmcnt(2)
	v_mfma_f32_16x16x32_bf16 v[172:175], v[188:191], v[160:163], v[176:179]
	s_waitcnt lgkmcnt(1)
	v_mfma_f32_16x16x32_bf16 v[104:107], v[192:195], v[164:167], v[104:107]
	s_waitcnt lgkmcnt(0)
	v_mfma_f32_16x16x32_bf16 v[172:175], v[206:209], v[168:171], v[172:175]
	s_nop 7
	v_pk_add_f32 v[72:73], v[106:107], v[174:175]
	v_pk_add_f32 v[104:105], v[104:105], v[172:173]
	ds_read_b128 v[106:109], v147 offset:4608
	ds_read_b128 v[172:175], v147 offset:4672
	ds_read_b128 v[176:179], v148 offset:8704
	ds_read_b128 v[188:191], v148 offset:8768
	ds_read_b128 v[192:195], v148 offset:8832
	ds_read_b128 v[206:209], v148 offset:8896
	s_waitcnt lgkmcnt(5)
	v_mfma_f32_16x16x32_bf16 v[106:109], v[106:109], v[110:113], 0
	s_waitcnt lgkmcnt(3)
	v_mfma_f32_16x16x32_bf16 v[176:179], v[176:179], v[118:121], 0
	v_mfma_f32_16x16x32_bf16 v[106:109], v[172:175], v[114:117], v[106:109]
	s_waitcnt lgkmcnt(2)
	v_mfma_f32_16x16x32_bf16 v[172:175], v[188:191], v[160:163], v[176:179]
	s_waitcnt lgkmcnt(1)
	v_mfma_f32_16x16x32_bf16 v[176:179], v[192:195], v[164:167], v[106:109]
	s_waitcnt lgkmcnt(0)
	v_mfma_f32_16x16x32_bf16 v[172:175], v[206:209], v[168:171], v[172:175]
	s_nop 7
	v_pk_add_f32 v[106:107], v[178:179], v[174:175]
	v_pk_add_f32 v[108:109], v[176:177], v[172:173]
	ds_read_b128 v[172:175], v147 offset:6912
	ds_read_b128 v[176:179], v147 offset:6976
	ds_read_b128 v[188:191], v148 offset:13056
	ds_read_b128 v[192:195], v148 offset:13120
	ds_read_b128 v[206:209], v148 offset:13184
	ds_read_b128 v[210:213], v148 offset:13248
	s_waitcnt lgkmcnt(5)
	v_mfma_f32_16x16x32_bf16 v[110:113], v[172:175], v[110:113], 0
	v_mul_f32_e32 v67, v71, v71
	v_fmac_f32_e32 v67, v70, v70
	v_fmac_f32_e32 v67, v68, v68
	s_waitcnt lgkmcnt(3)
	v_mfma_f32_16x16x32_bf16 v[118:121], v[188:191], v[118:121], 0
	v_fmac_f32_e32 v67, v69, v69
	v_mfma_f32_16x16x32_bf16 v[110:113], v[176:179], v[114:117], v[110:113]
	s_waitcnt lgkmcnt(2)
	v_mfma_f32_16x16x32_bf16 v[114:117], v[192:195], v[160:163], v[118:121]
	s_waitcnt lgkmcnt(1)
	v_mfma_f32_16x16x32_bf16 v[118:121], v[206:209], v[164:167], v[110:113]
	s_waitcnt lgkmcnt(0)
	v_mfma_f32_16x16x32_bf16 v[112:115], v[210:213], v[168:171], v[114:117]
	s_nop 7
	v_pk_add_f32 v[110:111], v[120:121], v[114:115]
	v_mul_f32_e32 v114, v105, v105
	v_fmac_f32_e32 v114, v104, v104
	v_fmac_f32_e32 v114, v72, v72
	v_fmac_f32_e32 v114, v73, v73
	v_add_f32_e32 v67, v67, v114
	v_mul_f32_e32 v114, v109, v109
	v_fmac_f32_e32 v114, v108, v108
	v_fmac_f32_e32 v114, v106, v106
	v_pk_add_f32 v[112:113], v[118:119], v[112:113]
	v_fmac_f32_e32 v114, v107, v107
	v_add_f32_e32 v67, v67, v114
	v_mul_f32_e32 v114, v113, v113
	v_fmac_f32_e32 v114, v112, v112
	v_fmac_f32_e32 v114, v110, v110
	v_fmac_f32_e32 v114, v111, v111
	v_and_b32_e32 v115, 64, v200
	v_add_f32_e32 v67, v67, v114
	v_xor_b32_e32 v114, 16, v200
	v_add_u32_e32 v115, 64, v115
	v_cmp_lt_i32_e32 vcc, v114, v115
	s_nop 1
	v_cndmask_b32_e32 v114, v200, v114, vcc
	v_lshlrev_b32_e32 v114, 2, v114
	ds_bpermute_b32 v114, v114, v67
	s_waitcnt lgkmcnt(0)
	v_add_f32_e32 v67, v67, v114
	v_xor_b32_e32 v114, 32, v200
	v_cmp_lt_i32_e32 vcc, v114, v115
	s_nop 1
	v_cndmask_b32_e32 v114, v200, v114, vcc
	v_lshlrev_b32_e32 v114, 2, v114
	ds_bpermute_b32 v114, v114, v67
	s_and_saveexec_b64 s[6:7], s[86:87]
	s_cbranch_execz .LBB0_1168
	s_waitcnt lgkmcnt(0)
	v_add_f32_e32 v67, v67, v114
	ds_write_b32 v135, v67
	s_branch .LBB0_1168
